# PEER per-token gather prologue: the hidden-row loads and expert-scale loads (previously seven dependent load->wait steps) are put in flight together
# speedup vs baseline: 1.1913x; 1.0103x over previous
.LBB0_869:
	ds_read2st64_b32 v[4:5], v220 offset0:12 offset1:13
	ds_read2st64_b32 v[6:7], v220 offset0:14 offset1:15
	v_mov_b32_e32 v10, 0
	v_mov_b32_e32 v11, 0
	s_mov_b32 s0, 0
	s_waitcnt lgkmcnt(0)
	v_lshrrev_b32_e32 v8, 11, v4
	v_lshrrev_b32_e32 v9, 11, v5
	v_cmp_eq_u32_e64 s[42:43], 0, v8
	v_cmp_eq_u32_e64 s[100:101], 0, v9
	s_bcnt1_i32_b64 s1, s[42:43]
	s_bcnt1_i32_b64 s41, s[100:101]
	v_mbcnt_lo_u32_b32 v12, s42, 0
	v_mbcnt_hi_u32_b32 v12, s43, v12
	v_mbcnt_lo_u32_b32 v13, s100, 0
	v_mbcnt_hi_u32_b32 v13, s101, v13
	s_add_i32 s98, s0, s1
	v_add_u32_e32 v12, s0, v12
	v_add_u32_e32 v13, s98, v13
	v_cndmask_b32_e64 v10, v10, v12, s[42:43]
	v_cndmask_b32_e64 v11, v11, v13, s[100:101]
	s_add_i32 s0, s98, s41
	v_cmp_eq_u32_e64 s[42:43], 1, v8
	v_cmp_eq_u32_e64 s[100:101], 1, v9
	s_bcnt1_i32_b64 s1, s[42:43]
	s_bcnt1_i32_b64 s41, s[100:101]
	v_mbcnt_lo_u32_b32 v12, s42, 0
	v_mbcnt_hi_u32_b32 v12, s43, v12
	v_mbcnt_lo_u32_b32 v13, s100, 0
	v_mbcnt_hi_u32_b32 v13, s101, v13
	s_add_i32 s98, s0, s1
	v_add_u32_e32 v12, s0, v12
	v_add_u32_e32 v13, s98, v13
	v_cndmask_b32_e64 v10, v10, v12, s[42:43]
	v_cndmask_b32_e64 v11, v11, v13, s[100:101]
	s_add_i32 s0, s98, s41
	v_cmp_eq_u32_e64 s[42:43], 2, v8
	v_cmp_eq_u32_e64 s[100:101], 2, v9
	s_bcnt1_i32_b64 s1, s[42:43]
	s_bcnt1_i32_b64 s41, s[100:101]
	v_mbcnt_lo_u32_b32 v12, s42, 0
	v_mbcnt_hi_u32_b32 v12, s43, v12
	v_mbcnt_lo_u32_b32 v13, s100, 0
	v_mbcnt_hi_u32_b32 v13, s101, v13
	s_add_i32 s98, s0, s1
	v_add_u32_e32 v12, s0, v12
	v_add_u32_e32 v13, s98, v13
	v_cndmask_b32_e64 v10, v10, v12, s[42:43]
	v_cndmask_b32_e64 v11, v11, v13, s[100:101]
	s_add_i32 s0, s98, s41
	v_cmp_eq_u32_e64 s[42:43], 3, v8
	v_cmp_eq_u32_e64 s[100:101], 3, v9
	s_bcnt1_i32_b64 s1, s[42:43]
	s_bcnt1_i32_b64 s41, s[100:101]
	v_mbcnt_lo_u32_b32 v12, s42, 0
	v_mbcnt_hi_u32_b32 v12, s43, v12
	v_mbcnt_lo_u32_b32 v13, s100, 0
	v_mbcnt_hi_u32_b32 v13, s101, v13
	s_add_i32 s98, s0, s1
	v_add_u32_e32 v12, s0, v12
	v_add_u32_e32 v13, s98, v13
	v_cndmask_b32_e64 v10, v10, v12, s[42:43]
	v_cndmask_b32_e64 v11, v11, v13, s[100:101]
	s_add_i32 s0, s98, s41
	v_cmp_eq_u32_e64 s[42:43], 4, v8
	v_cmp_eq_u32_e64 s[100:101], 4, v9
	s_bcnt1_i32_b64 s1, s[42:43]
	s_bcnt1_i32_b64 s41, s[100:101]
	v_mbcnt_lo_u32_b32 v12, s42, 0
	v_mbcnt_hi_u32_b32 v12, s43, v12
	v_mbcnt_lo_u32_b32 v13, s100, 0
	v_mbcnt_hi_u32_b32 v13, s101, v13
	s_add_i32 s98, s0, s1
	v_add_u32_e32 v12, s0, v12
	v_add_u32_e32 v13, s98, v13
	v_cndmask_b32_e64 v10, v10, v12, s[42:43]
	v_cndmask_b32_e64 v11, v11, v13, s[100:101]
	s_add_i32 s0, s98, s41
	v_cmp_eq_u32_e64 s[42:43], 5, v8
	v_cmp_eq_u32_e64 s[100:101], 5, v9
	s_bcnt1_i32_b64 s1, s[42:43]
	s_bcnt1_i32_b64 s41, s[100:101]
	v_mbcnt_lo_u32_b32 v12, s42, 0
	v_mbcnt_hi_u32_b32 v12, s43, v12
	v_mbcnt_lo_u32_b32 v13, s100, 0
	v_mbcnt_hi_u32_b32 v13, s101, v13
	s_add_i32 s98, s0, s1
	v_add_u32_e32 v12, s0, v12
	v_add_u32_e32 v13, s98, v13
	v_cndmask_b32_e64 v10, v10, v12, s[42:43]
	v_cndmask_b32_e64 v11, v11, v13, s[100:101]
	s_add_i32 s0, s98, s41
	v_cmp_eq_u32_e64 s[42:43], 6, v8
	v_cmp_eq_u32_e64 s[100:101], 6, v9
	s_bcnt1_i32_b64 s1, s[42:43]
	s_bcnt1_i32_b64 s41, s[100:101]
	v_mbcnt_lo_u32_b32 v12, s42, 0
	v_mbcnt_hi_u32_b32 v12, s43, v12
	v_mbcnt_lo_u32_b32 v13, s100, 0
	v_mbcnt_hi_u32_b32 v13, s101, v13
	s_add_i32 s98, s0, s1
	v_add_u32_e32 v12, s0, v12
	v_add_u32_e32 v13, s98, v13
	v_cndmask_b32_e64 v10, v10, v12, s[42:43]
	v_cndmask_b32_e64 v11, v11, v13, s[100:101]
	s_add_i32 s0, s98, s41
	v_cmp_eq_u32_e64 s[42:43], 7, v8
	v_cmp_eq_u32_e64 s[100:101], 7, v9
	s_bcnt1_i32_b64 s1, s[42:43]
	s_bcnt1_i32_b64 s41, s[100:101]
	v_mbcnt_lo_u32_b32 v12, s42, 0
	v_mbcnt_hi_u32_b32 v12, s43, v12
	v_mbcnt_lo_u32_b32 v13, s100, 0
	v_mbcnt_hi_u32_b32 v13, s101, v13
	s_add_i32 s98, s0, s1
	v_add_u32_e32 v12, s0, v12
	v_add_u32_e32 v13, s98, v13
	v_cndmask_b32_e64 v10, v10, v12, s[42:43]
	v_cndmask_b32_e64 v11, v11, v13, s[100:101]
	s_add_i32 s0, s98, s41
	s_and_b32 s1, s19, 1
	s_mul_i32 s1, s1, 0x7f
	v_xor_b32_e32 v10, s1, v10
	v_xor_b32_e32 v11, s1, v11
	v_lshl_add_u32 v10, v10, 2, v199
	v_lshl_add_u32 v11, v11, 2, v199
	ds_write_b32 v10, v4
	ds_write_b32 v11, v5
	ds_write_b32 v10, v6 offset:512
	ds_write_b32 v11, v7 offset:512
	v_add_u32_e32 v0, s48, v0
	v_cmp_gt_i32_e32 vcc, s52, v0
	v_mov_b32_e32 v2, s49
	v_mov_b32_e32 v3, s50
	v_cndmask_b32_e32 v2, v2, v3, vcc
	v_add_u32_e32 v152, v0, v2
	v_ashrrev_i32_e32 v153, 31, v152
	v_lshlrev_b64 v[2:3], 11, v[152:153]
	v_lshl_add_u64 v[2:3], v[138:139], 0, v[2:3]
	global_load_dwordx2 v[4:5], v[2:3], off
	global_load_dwordx2 v[6:7], v[2:3], off offset:512
	global_load_dwordx2 v[10:11], v[2:3], off offset:1024
	global_load_dwordx2 v[12:13], v[2:3], off offset:1536
	s_lshl_b32 s0, s19, 10
	v_add3_u32 v9, v131, s0, v136
	ds_read2st64_b32 v[14:15], v220 offset0:12 offset1:13
	ds_read2st64_b32 v[16:17], v220 offset0:14 offset1:15
	v_mov_b32_e32 v184, 0
	s_mov_b32 s1, 0
	v_mov_b32_e32 v185, v184
	v_mov_b32_e32 v186, v184
	v_mov_b32_e32 v187, v184
	v_mov_b32_e32 v182, v184
	v_mov_b32_e32 v183, v184
	v_mov_b32_e32 v180, v184
	v_mov_b32_e32 v181, v184
	v_mov_b32_e32 v178, v184
	v_mov_b32_e32 v179, v184
	v_mov_b32_e32 v176, v184
	v_mov_b32_e32 v177, v184
	v_mov_b32_e32 v174, v184
	v_mov_b32_e32 v175, v184
	v_mov_b32_e32 v172, v184
	v_mov_b32_e32 v173, v184
	s_waitcnt lgkmcnt(0)
	v_mov_b32_e32 v0, v14
	v_lshlrev_b64 v[18:19], 2, v[0:1]
	v_lshl_add_u64 v[20:21], s[34:35], 0, v[18:19]
	v_lshl_add_u64 v[18:19], s[90:91], 0, v[18:19]
	global_load_dword v8, v[20:21], off
	global_load_dword v22, v[18:19], off
	v_mov_b32_e32 v0, v15
	v_lshlrev_b64 v[18:19], 2, v[0:1]
	v_lshl_add_u64 v[20:21], s[34:35], 0, v[18:19]
	v_lshl_add_u64 v[18:19], s[90:91], 0, v[18:19]
	global_load_dword v23, v[20:21], off
	global_load_dword v24, v[18:19], off
	s_waitcnt vmcnt(0)
	v_lshlrev_b32_e32 v154, 16, v4
	v_and_b32_e32 v155, 0xffff0000, v4
	v_lshlrev_b32_e32 v156, 16, v5
	v_and_b32_e32 v157, 0xffff0000, v5
	v_lshlrev_b32_e32 v158, 16, v6
	v_and_b32_e32 v159, 0xffff0000, v6
	v_lshlrev_b32_e32 v162, 16, v7
	v_and_b32_e32 v163, 0xffff0000, v7
	v_lshlrev_b32_e32 v164, 16, v10
	v_and_b32_e32 v165, 0xffff0000, v10
	v_lshlrev_b32_e32 v166, 16, v11
	v_and_b32_e32 v167, 0xffff0000, v11
	v_lshlrev_b32_e32 v168, 16, v12
	v_and_b32_e32 v169, 0xffff0000, v12
	v_lshlrev_b32_e32 v170, 16, v13
	v_and_b32_e32 v171, 0xffff0000, v13
	v_mul_f32_e32 v6, v16, v22
	v_mul_f32_e32 v0, v17, v24
	ds_write2st64_b32 v9, v8, v23 offset1:1
	ds_write2st64_b32 v9, v6, v0 offset0:2 offset1:3
